# attention: K/V tile loads with wave-uniform SGPR bases + 32-bit lane offsets (no per-tile 64-bit VALU address arithmetic); row-sum chains start without the add of zero
# speedup vs baseline: 1.0133x; 1.0039x over previous
; __global__ void __launch_bounds__(NTHR, 2) mega(Args args) {
;     ...
;     if (IN(3)) { for (int rep = 0; rep < (MK_DUP == 3 ? 2 : 1); ++rep) {
;         __syncthreads();
;         const bf16* DQb = (const bf16*)(ws + WS_DQ); const bf16* DKb = (const bf16*)(ws + WS_DK); const bf16* DVb = (const bf16*)(ws + WS_DV); bf16* ODb = (bf16*)(ws + WS_OD);
;         for (int idx = blockIdx.x; idx < 512; idx += G) {
;             const int b = idx & 7, rest = idx >> 3, hp = rest >> 3, qb = rest & 7;
;             att::attn_unit(DQb + ((size_t)(b * 8 + hp) * L + qb * 256) * 64, DKb + (size_t)(b * 8 + hp) * LT * 64, DVb + (size_t)(b * 4 + (hp >> 1)) * LT * 128,
;                            ODb + ((size_t)(b * 8 + hp) * L + qb * 256) * 128, LT, (char*)lds_raw);
.LBB0_526:
	s_cmp_lt_i32 s74, 4
	s_cselect_b64 s[0:1], -1, 0
	s_and_b64 s[8:9], s[0:1], s[4:5]
	s_andn2_b64 vcc, exec, s[8:9]
	s_cbranch_vccnz .LBB0_544
	s_cmpk_gt_i32 s2, 0x1ff
	s_waitcnt vmcnt(0)
	s_barrier
	s_cbranch_scc1 .LBB0_534
	s_add_u32 s3, s30, 0xa700000
	s_addc_u32 s14, s31, 0
	s_add_u32 s15, s30, 0xb700000
	s_addc_u32 s16, s31, 0
	s_add_u32 s17, s30, 0xc900000
	s_addc_u32 s19, s31, 0
	v_mov_b32_e32 v138, 0
	s_movk_i32 s22, 0x70
	s_movk_i32 s23, 0x2000
	s_movk_i32 s34, 0x4000
	s_movk_i32 s35, 0x6000
	v_mov_b32_e32 v1, 0x48000
	v_mov_b32_e32 v152, 0x90000
	s_mov_b32 s40, 0xc908000
	s_mov_b32 s41, 0xc90a000
	s_mov_b32 s42, 0xb704000
	s_mov_b32 s43, 0xc90c000
	s_mov_b32 s46, 0xc90e000
	s_mov_b32 s47, 0xb706000
	s_add_u32 s80, s30, 0xc908000
	s_addc_u32 s81, s31, 0
	s_add_u32 s82, s30, 0xc90a000
	s_addc_u32 s83, s31, 0
	s_add_u32 s84, s30, 0xb704000
	s_addc_u32 s85, s31, 0
	s_add_u32 s86, s30, 0xc90c000
	s_addc_u32 s87, s31, 0
	s_add_u32 s88, s30, 0xc90e000
	s_addc_u32 s89, s31, 0
	s_add_u32 s90, s30, 0xb706000
	s_addc_u32 s91, s31, 0
	s_mov_b64 s[0:1], 0x4000
	s_mov_b64 s[4:5], 0x8000
	s_movk_i32 s48, 0x7fff
	s_mov_b32 s49, s2
	s_mov_b32 s50, s2
	s_branch .LBB0_530

; #define SBAR() __builtin_amdgcn_sched_barrier(0)
; #define SLOAD(i, k0) do { const char* vt_ = (const char*)Vh + (size_t)(k0) * 256; const char* kt_ = (const char*)Kh + (size_t)(k0) * 128; \
;     sr_[i].vs0 = *reinterpret_cast<const bf16x8*>(vt_ + voff0); sr_[i].vs1 = *reinterpret_cast<const bf16x8*>(vt_ + 32 * 256 + voff0); \
;     sr_[i].ks0 = *reinterpret_cast<const bf16x8*>(kt_ + koff0); } while (0)
; #define SBAR() __builtin_amdgcn_sched_barrier(0)
; __device__ __forceinline__ void attn_unit(const bf16* __restrict__ Qb, const bf16* __restrict__ Kh, const bf16* __restrict__ Vh, bf16* __restrict__ Ob, int seq, char* lds) {
;     ...
;         SBAR(); qkt(pB0, pB1, K_lds + SHM_K, qr, r32, hi); pv_ks<0>(o, vb0, pa0); SBAR();
;         softHalf(pA1, l_reg, pa2, pa3); SBAR();
;         SLOAD(SO, (j + 1) * KVBLK); SBAR();
;         pv_ks<1>(o, vb0, pa1); pv_ks<2>(o, vb0, pa2); pv_ks<3>(o, vb0, pa3); SBAR();
;         softHalf(pB0, l_reg, pa0, pa1); SBAR();
.LBB0_531:
	ds_read_b128 v[82:85], v157 offset:40960
	ds_read_b128 v[86:89], v157 offset:45056
	ds_read_b128 v[164:167], v159 offset:40960
	ds_read_b128 v[168:171], v159 offset:45056
	ds_read_b128 v[188:191], v162 offset:40960
	ds_read_b128 v[230:233], v162 offset:45056
	ds_read_b128 v[234:237], v163 offset:40960
	ds_read_b128 v[242:245], v163 offset:45056
	v_exp_f32_e32 v66, v66
	v_exp_f32_e32 v67, v67
	v_exp_f32_e32 v68, v68
	s_waitcnt lgkmcnt(7)
	v_mfma_f32_32x32x16_bf16 v[98:113], v[82:85], v[126:129], 0
	v_exp_f32_e32 v69, v69
	v_exp_f32_e32 v70, v70
	v_exp_f32_e32 v71, v71
	s_waitcnt lgkmcnt(6)
	v_mfma_f32_32x32x16_bf16 v[82:97], v[86:89], v[126:129], 0
	v_add_f32_e32 v179, v67, v66
	v_exp_f32_e32 v72, v72
	v_add_f32_e32 v179, v68, v179
	s_waitcnt lgkmcnt(5)
	v_mfma_f32_32x32x16_bf16 v[98:113], v[164:167], v[122:125], v[98:113]
	v_exp_f32_e32 v73, v73
	v_add_f32_e32 v179, v69, v179
	v_exp_f32_e32 v74, v74
	s_waitcnt lgkmcnt(4)
	v_mfma_f32_32x32x16_bf16 v[82:97], v[168:171], v[122:125], v[82:97]
	ds_read_b64_tr_b16 v[172:173], v156 offset:0
	ds_read_b64_tr_b16 v[174:175], v156 offset:0x800
	ds_read_b64_tr_b16 v[164:165], v156 offset:0x200
	ds_read_b64_tr_b16 v[166:167], v156 offset:0xa00
	ds_read_b64_tr_b16 v[180:181], v156 offset:0x400
	ds_read_b64_tr_b16 v[182:183], v156 offset:0xc00
	ds_read_b64_tr_b16 v[184:185], v156 offset:0x600
	ds_read_b64_tr_b16 v[186:187], v156 offset:0xe00
	v_add_f32_e32 v179, v70, v179
	v_exp_f32_e32 v75, v75
	v_add_f32_e32 v179, v71, v179
	s_waitcnt lgkmcnt(11)
	v_mfma_f32_32x32x16_bf16 v[98:113], v[188:191], v[118:121], v[98:113]
	v_exp_f32_e32 v76, v76
	v_add_f32_e32 v179, v72, v179
	v_exp_f32_e32 v77, v77
	s_waitcnt lgkmcnt(10)
	v_mfma_f32_32x32x16_bf16 v[82:97], v[230:233], v[118:121], v[82:97]
	v_add_f32_e32 v179, v73, v179
	v_exp_f32_e32 v78, v78
	v_add_f32_e32 v179, v74, v179
	s_waitcnt lgkmcnt(9)
	v_mfma_f32_32x32x16_bf16 v[98:113], v[234:237], v[114:117], v[98:113]
	v_exp_f32_e32 v79, v79
	v_add_f32_e32 v179, v75, v179
	v_exp_f32_e32 v80, v80
	s_waitcnt lgkmcnt(8)
	v_mfma_f32_32x32x16_bf16 v[82:97], v[242:245], v[114:117], v[82:97]
	v_add_f32_e32 v179, v76, v179
	v_exp_f32_e32 v81, v81
	v_add_f32_e32 v179, v77, v179
	v_add_f32_e32 v179, v78, v179
	s_waitcnt lgkmcnt(6)
	v_mfma_f32_32x32x16_bf16 v[2:17], v[134:137], v[172:175], v[2:17]
	ds_read_b64_tr_b16 v[188:189], v156 offset:0x1000
	ds_read_b64_tr_b16 v[190:191], v156 offset:0x1800
	ds_read_b64_tr_b16 v[230:231], v156 offset:0x1200
	ds_read_b64_tr_b16 v[232:233], v156 offset:0x1a00
	ds_read_b64_tr_b16 v[234:235], v156 offset:0x1400
	ds_read_b64_tr_b16 v[236:237], v156 offset:0x1c00
	ds_read_b64_tr_b16 v[242:243], v156 offset:0x1600
	ds_read_b64_tr_b16 v[244:245], v156 offset:0x1e00
	v_add_f32_e32 v179, v79, v179
	v_add_f32_e32 v179, v80, v179
	v_add_f32_e32 v179, v81, v179
	v_cvt_pk_bf16_f32 v66, v66, v67
	s_waitcnt lgkmcnt(12)
	v_mfma_f32_32x32x16_bf16 v[18:33], v[134:137], v[164:167], v[18:33]
	v_cvt_pk_bf16_f32 v67, v68, v69
	v_cvt_pk_bf16_f32 v68, v70, v71
	v_cvt_pk_bf16_f32 v69, v72, v73
	v_cvt_pk_bf16_f32 v70, v74, v75
	s_waitcnt lgkmcnt(10)
	v_mfma_f32_32x32x16_bf16 v[34:49], v[134:137], v[180:183], v[34:49]
	v_cvt_pk_bf16_f32 v71, v76, v77
	v_cvt_pk_bf16_f32 v72, v78, v79
	v_cvt_pk_bf16_f32 v73, v80, v81
	v_add_f32_e32 v221, v139, v179
	s_waitcnt lgkmcnt(8)
	v_mfma_f32_32x32x16_bf16 v[50:65], v[134:137], v[184:187], v[50:65]
	global_load_dwordx4 v[74:77], v148, s[80:81]
	global_load_dwordx4 v[78:81], v148, s[82:83]
	global_load_dwordx4 v[164:167], v146, s[84:85]
	v_exp_f32_e32 v220, v98
	v_exp_f32_e32 v177, v99
	s_waitcnt lgkmcnt(6)
	v_mfma_f32_32x32x16_bf16 v[2:17], v[130:133], v[188:191], v[2:17]
	ds_read_b64_tr_b16 v[168:169], v156 offset:0x2000
	ds_read_b64_tr_b16 v[170:171], v156 offset:0x2800
	ds_read_b64_tr_b16 v[172:173], v156 offset:0x2200
	ds_read_b64_tr_b16 v[174:175], v156 offset:0x2a00
	ds_read_b64_tr_b16 v[180:181], v156 offset:0x2400
	ds_read_b64_tr_b16 v[182:183], v156 offset:0x2c00
	ds_read_b64_tr_b16 v[184:185], v156 offset:0x2600
	ds_read_b64_tr_b16 v[186:187], v156 offset:0x2e00
	v_exp_f32_e32 v193, v100
	v_exp_f32_e32 v195, v101
	v_exp_f32_e32 v197, v102
	s_waitcnt lgkmcnt(12)
	v_mfma_f32_32x32x16_bf16 v[18:33], v[130:133], v[230:233], v[18:33]
	v_exp_f32_e32 v199, v103
	v_exp_f32_e32 v201, v104
	s_waitcnt lgkmcnt(10)
	v_mfma_f32_32x32x16_bf16 v[34:49], v[130:133], v[234:237], v[34:49]
	v_exp_f32_e32 v203, v105
	v_cvt_pk_bf16_f32 v222, v220, v177
	v_cvt_pk_bf16_f32 v223, v193, v195
	s_waitcnt lgkmcnt(8)
	v_mfma_f32_32x32x16_bf16 v[50:65], v[130:133], v[242:245], v[50:65]
	v_cvt_pk_bf16_f32 v224, v197, v199
	v_cvt_pk_bf16_f32 v225, v201, v203
	v_exp_f32_e32 v205, v106
	s_waitcnt lgkmcnt(6)
	v_mfma_f32_32x32x16_bf16 v[2:17], v[66:69], v[168:171], v[2:17]
	ds_read_b64_tr_b16 v[188:189], v156 offset:0x3000
	ds_read_b64_tr_b16 v[190:191], v156 offset:0x3800
	ds_read_b64_tr_b16 v[230:231], v156 offset:0x3200
	ds_read_b64_tr_b16 v[232:233], v156 offset:0x3a00
	ds_read_b64_tr_b16 v[234:235], v156 offset:0x3400
	ds_read_b64_tr_b16 v[236:237], v156 offset:0x3c00
	ds_read_b64_tr_b16 v[242:243], v156 offset:0x3600
	ds_read_b64_tr_b16 v[244:245], v156 offset:0x3e00
	v_exp_f32_e32 v207, v107
	v_exp_f32_e32 v209, v108
	v_exp_f32_e32 v211, v109
	s_waitcnt lgkmcnt(12)
	v_mfma_f32_32x32x16_bf16 v[18:33], v[66:69], v[172:175], v[18:33]
	v_exp_f32_e32 v213, v110
	v_exp_f32_e32 v215, v111
	s_waitcnt lgkmcnt(10)
	v_mfma_f32_32x32x16_bf16 v[34:49], v[66:69], v[180:183], v[34:49]
	v_exp_f32_e32 v217, v112
	v_exp_f32_e32 v219, v113
	v_add_f32_e32 v238, v177, v220
	s_waitcnt lgkmcnt(8)
	v_mfma_f32_32x32x16_bf16 v[50:65], v[66:69], v[184:187], v[50:65]
	s_waitcnt lgkmcnt(0)
	s_barrier
; #define SBAR() __builtin_amdgcn_sched_barrier(0)
; #define SLOAD(i, k0) do { const char* vt_ = (const char*)Vh + (size_t)(k0) * 256; const char* kt_ = (const char*)Kh + (size_t)(k0) * 128; \
;     sr_[i].vs0 = *reinterpret_cast<const bf16x8*>(vt_ + voff0); sr_[i].vs1 = *reinterpret_cast<const bf16x8*>(vt_ + 32 * 256 + voff0); \
;     sr_[i].ks0 = *reinterpret_cast<const bf16x8*>(kt_ + koff0); } while (0)
; #define SWRITE(b, i) do { *(bf16x8*)(V_lds + (b) * SHM_V + vst0) = sr_[i].vs0; *(bf16x8*)(V_lds + (b) * SHM_V + vst1) = sr_[i].vs1; \
;     *(bf16x8*)(K_lds + (b) * SHM_K + kst) = sr_[i].ks0; } while (0)
; #define SWAIT() asm volatile("s_waitcnt vmcnt(0)" ::: "memory")
; #define SBAR() __builtin_amdgcn_sched_barrier(0)
; __device__ __forceinline__ void attn_unit(const bf16* __restrict__ Qb, const bf16* __restrict__ Kh, const bf16* __restrict__ Vh, bf16* __restrict__ Ob, int seq, char* lds) {
;     ...
;         __syncthreads(); SWAIT(); SWRITE(0, SE);
;         __syncthreads();
;         SBAR(); qkt(pA0, pA1, K_lds, qr, r32, hi); pv_ks<0>(o, vb0 + SHM_V, pa0); SBAR();
;         softHalf(pB1, l_reg, pa2, pa3); SBAR();
;         SLOAD(SE, (j + 2) * KVBLK); SBAR();
;         pv_ks<1>(o, vb0 + SHM_V, pa1); pv_ks<2>(o, vb0 + SHM_V, pa2); pv_ks<3>(o, vb0 + SHM_V, pa3); SBAR();
;         softHalf(pA0, l_reg, pa0, pa1); SBAR();
	s_waitcnt vmcnt(0)
	s_waitcnt vmcnt(2)
	ds_write_b128 v160, v[74:77]
	s_waitcnt vmcnt(1)
	ds_write_b128 v161, v[78:81]
	s_waitcnt vmcnt(0)
	ds_write_b128 v158, v[164:167] offset:32768
	v_add_f32_e32 v238, v193, v238
	v_add_f32_e32 v238, v195, v238
	v_add_f32_e32 v238, v197, v238
	v_add_f32_e32 v238, v199, v238
	v_add_f32_e32 v238, v201, v238
	v_mfma_f32_32x32x16_bf16 v[2:17], v[70:73], v[188:191], v[2:17]
	v_add_f32_e32 v238, v203, v238
	v_add_f32_e32 v238, v205, v238
	v_add_f32_e32 v238, v207, v238
	v_add_f32_e32 v238, v209, v238
	v_add_f32_e32 v238, v211, v238
	v_mfma_f32_32x32x16_bf16 v[18:33], v[70:73], v[230:233], v[18:33]
	v_add_f32_e32 v238, v213, v238
	v_add_f32_e32 v238, v215, v238
	v_add_f32_e32 v238, v217, v238
	v_add_f32_e32 v238, v219, v238
	v_add_f32_e32 v238, v221, v238
	v_mfma_f32_32x32x16_bf16 v[34:49], v[70:73], v[234:237], v[34:49]
	v_cvt_pk_bf16_f32 v226, v205, v207
	v_cvt_pk_bf16_f32 v227, v209, v211
	v_cvt_pk_bf16_f32 v228, v213, v215
	v_cvt_pk_bf16_f32 v229, v217, v219
	v_mfma_f32_32x32x16_bf16 v[50:65], v[70:73], v[242:245], v[50:65]
	s_waitcnt lgkmcnt(0)
	s_barrier
	ds_read_b128 v[66:69], v157 offset:32768
	ds_read_b128 v[70:73], v157 offset:36864
	ds_read_b128 v[164:167], v159 offset:32768
	ds_read_b128 v[172:175], v159 offset:36864
	ds_read_b128 v[230:233], v162 offset:32768
	ds_read_b128 v[234:237], v162 offset:36864
	ds_read_b128 v[168:171], v163 offset:32768
	ds_read_b128 v[242:245], v163 offset:36864
	v_exp_f32_e32 v176, v82
	v_exp_f32_e32 v192, v83
	v_exp_f32_e32 v194, v84
	s_waitcnt lgkmcnt(7)
	v_mfma_f32_32x32x16_bf16 v[98:113], v[66:69], v[126:129], 0
	v_exp_f32_e32 v196, v85
	v_exp_f32_e32 v198, v86
	v_exp_f32_e32 v200, v87
	s_waitcnt lgkmcnt(6)
	v_mfma_f32_32x32x16_bf16 v[66:81], v[70:73], v[126:129], 0
	v_add_f32_e32 v82, v192, v176
	v_exp_f32_e32 v202, v88
	v_add_f32_e32 v82, v194, v82
	s_waitcnt lgkmcnt(5)
	v_mfma_f32_32x32x16_bf16 v[98:113], v[164:167], v[122:125], v[98:113]
	v_exp_f32_e32 v204, v89
	v_add_f32_e32 v82, v196, v82
	v_exp_f32_e32 v206, v90
	s_waitcnt lgkmcnt(4)
	v_mfma_f32_32x32x16_bf16 v[66:81], v[172:175], v[122:125], v[66:81]
	ds_read_b64_tr_b16 v[180:181], v141 offset:0
	ds_read_b64_tr_b16 v[182:183], v141 offset:0x800
	ds_read_b64_tr_b16 v[164:165], v141 offset:0x200
	ds_read_b64_tr_b16 v[166:167], v141 offset:0xa00
	ds_read_b64_tr_b16 v[184:185], v141 offset:0x400
	ds_read_b64_tr_b16 v[186:187], v141 offset:0xc00
	ds_read_b64_tr_b16 v[188:189], v141 offset:0x600
	ds_read_b64_tr_b16 v[190:191], v141 offset:0xe00
	v_add_f32_e32 v82, v198, v82
	v_exp_f32_e32 v208, v91
	v_add_f32_e32 v82, v200, v82
	s_waitcnt lgkmcnt(11)
	v_mfma_f32_32x32x16_bf16 v[98:113], v[230:233], v[118:121], v[98:113]
	v_exp_f32_e32 v210, v92
	v_add_f32_e32 v82, v202, v82
	v_exp_f32_e32 v212, v93
	s_waitcnt lgkmcnt(10)
	v_mfma_f32_32x32x16_bf16 v[66:81], v[234:237], v[118:121], v[66:81]
	v_add_f32_e32 v82, v204, v82
	v_exp_f32_e32 v214, v94
	v_add_f32_e32 v82, v206, v82
	s_waitcnt lgkmcnt(9)
	v_mfma_f32_32x32x16_bf16 v[98:113], v[168:171], v[114:117], v[98:113]
	v_exp_f32_e32 v216, v95
	v_add_f32_e32 v82, v208, v82
	v_exp_f32_e32 v218, v96
	s_waitcnt lgkmcnt(8)
	v_mfma_f32_32x32x16_bf16 v[66:81], v[242:245], v[114:117], v[66:81]
	v_add_f32_e32 v82, v210, v82
	v_exp_f32_e32 v220, v97
	v_add_f32_e32 v82, v212, v82
	v_add_f32_e32 v82, v214, v82
	s_waitcnt lgkmcnt(6)
	v_mfma_f32_32x32x16_bf16 v[2:17], v[222:225], v[180:183], v[2:17]
	ds_read_b64_tr_b16 v[230:231], v141 offset:0x1000
	ds_read_b64_tr_b16 v[232:233], v141 offset:0x1800
	ds_read_b64_tr_b16 v[234:235], v141 offset:0x1200
	ds_read_b64_tr_b16 v[236:237], v141 offset:0x1a00
	ds_read_b64_tr_b16 v[168:169], v141 offset:0x1400
	ds_read_b64_tr_b16 v[170:171], v141 offset:0x1c00
	ds_read_b64_tr_b16 v[172:173], v141 offset:0x1600
	ds_read_b64_tr_b16 v[174:175], v141 offset:0x1e00
	v_add_f32_e32 v82, v216, v82
	v_add_f32_e32 v82, v218, v82
	v_add_f32_e32 v82, v220, v82
	v_add_f32_e32 v139, v82, v238
	v_cvt_pk_bf16_f32 v82, v176, v192
	s_waitcnt lgkmcnt(12)
	v_mfma_f32_32x32x16_bf16 v[18:33], v[222:225], v[164:167], v[18:33]
	v_cvt_pk_bf16_f32 v83, v194, v196
	v_cvt_pk_bf16_f32 v84, v198, v200
	v_cvt_pk_bf16_f32 v85, v202, v204
	s_waitcnt lgkmcnt(10)
	v_mfma_f32_32x32x16_bf16 v[34:49], v[222:225], v[184:187], v[34:49]
	v_cvt_pk_bf16_f32 v86, v206, v208
	v_cvt_pk_bf16_f32 v87, v210, v212
	v_cvt_pk_bf16_f32 v88, v214, v216
	v_cvt_pk_bf16_f32 v89, v218, v220
	s_waitcnt lgkmcnt(8)
	v_mfma_f32_32x32x16_bf16 v[50:65], v[222:225], v[188:191], v[50:65]
	global_load_dwordx4 v[90:93], v148, s[86:87]
	global_load_dwordx4 v[94:97], v148, s[88:89]
	global_load_dwordx4 v[164:167], v146, s[90:91]
	v_exp_f32_e32 v239, v98
	v_exp_f32_e32 v241, v99
	s_waitcnt lgkmcnt(6)
	v_mfma_f32_32x32x16_bf16 v[2:17], v[226:229], v[230:233], v[2:17]
	ds_read_b64_tr_b16 v[180:181], v141 offset:0x2000
	ds_read_b64_tr_b16 v[182:183], v141 offset:0x2800
	ds_read_b64_tr_b16 v[184:185], v141 offset:0x2200
	ds_read_b64_tr_b16 v[186:187], v141 offset:0x2a00
	ds_read_b64_tr_b16 v[188:189], v141 offset:0x2400
	ds_read_b64_tr_b16 v[190:191], v141 offset:0x2c00
	ds_read_b64_tr_b16 v[222:223], v141 offset:0x2600
	ds_read_b64_tr_b16 v[224:225], v141 offset:0x2e00
	v_exp_f32_e32 v242, v100
	v_exp_f32_e32 v243, v101
	v_exp_f32_e32 v244, v102
	s_waitcnt lgkmcnt(12)
	v_mfma_f32_32x32x16_bf16 v[18:33], v[226:229], v[234:237], v[18:33]
	v_exp_f32_e32 v98, v106
	v_exp_f32_e32 v245, v103
	s_waitcnt lgkmcnt(10)
	v_mfma_f32_32x32x16_bf16 v[34:49], v[226:229], v[168:171], v[34:49]
	v_add_f32_e32 v106, v241, v239
	v_exp_f32_e32 v246, v104
	v_add_f32_e32 v106, v242, v106
	s_waitcnt lgkmcnt(8)
	v_mfma_f32_32x32x16_bf16 v[50:65], v[226:229], v[172:175], v[50:65]
	v_exp_f32_e32 v247, v105
	v_add_f32_e32 v106, v243, v106
	v_add_f32_e32 v106, v244, v106
	v_exp_f32_e32 v99, v107
	s_waitcnt lgkmcnt(6)
	v_mfma_f32_32x32x16_bf16 v[2:17], v[82:85], v[180:183], v[2:17]
	ds_read_b64_tr_b16 v[230:231], v141 offset:0x3000
	ds_read_b64_tr_b16 v[232:233], v141 offset:0x3800
	ds_read_b64_tr_b16 v[234:235], v141 offset:0x3200
	ds_read_b64_tr_b16 v[236:237], v141 offset:0x3a00
	ds_read_b64_tr_b16 v[168:169], v141 offset:0x3400
	ds_read_b64_tr_b16 v[170:171], v141 offset:0x3c00
	ds_read_b64_tr_b16 v[172:173], v141 offset:0x3600
	ds_read_b64_tr_b16 v[174:175], v141 offset:0x3e00
	v_add_f32_e32 v106, v245, v106
	v_exp_f32_e32 v100, v108
	v_add_f32_e32 v106, v246, v106
	s_waitcnt lgkmcnt(12)
	v_mfma_f32_32x32x16_bf16 v[18:33], v[82:85], v[184:187], v[18:33]
	v_exp_f32_e32 v101, v109
	v_add_f32_e32 v106, v247, v106
	v_exp_f32_e32 v102, v110
	v_add_f32_e32 v106, v98, v106
	s_waitcnt lgkmcnt(10)
	v_mfma_f32_32x32x16_bf16 v[34:49], v[82:85], v[188:191], v[34:49]
	v_exp_f32_e32 v103, v111
	v_add_f32_e32 v106, v99, v106
	v_exp_f32_e32 v104, v112
	s_waitcnt lgkmcnt(8)
	v_mfma_f32_32x32x16_bf16 v[50:65], v[82:85], v[222:225], v[50:65]
	s_waitcnt lgkmcnt(0)
	s_barrier
; #define SBAR() __builtin_amdgcn_sched_barrier(0)
; #define SWRITE(b, i) do { *(bf16x8*)(V_lds + (b) * SHM_V + vst0) = sr_[i].vs0; *(bf16x8*)(V_lds + (b) * SHM_V + vst1) = sr_[i].vs1; \
;     *(bf16x8*)(K_lds + (b) * SHM_K + kst) = sr_[i].ks0; } while (0)
; #define SWAIT() asm volatile("s_waitcnt vmcnt(0)" ::: "memory")
; #define SBAR() __builtin_amdgcn_sched_barrier(0)
; __device__ __forceinline__ void attn_unit(const bf16* __restrict__ Qb, const bf16* __restrict__ Kh, const bf16* __restrict__ Vh, bf16* __restrict__ Ob, int seq, char* lds) {
;     ...
;         __syncthreads(); SWAIT(); SWRITE(1, SO);
;         __syncthreads();
;     }
;     SBAR(); qkt(pB0, pB1, K_lds + SHM_K, qr, r32, hi); pv_ks<0>(o, vb0, pa0); SBAR();
;     softHalf(pA1, l_reg, pa2, pa3); SBAR();
;     pv_ks<1>(o, vb0, pa1); pv_ks<2>(o, vb0, pa2); pv_ks<3>(o, vb0, pa3); SBAR();
	s_waitcnt vmcnt(0)
	s_add_i32 s10, s10, 2
	v_add_u32_e32 v146, 0x4000, v146
	s_cmp_gt_u32 s10, 32
	v_add_u32_e32 v148, 0x8000, v148
	s_waitcnt vmcnt(2)
	ds_write_b128 v160, v[90:93] offset:16384
	s_waitcnt vmcnt(1)
	ds_write_b128 v161, v[94:97] offset:16384
	s_waitcnt vmcnt(0)
	ds_write_b128 v158, v[164:167] offset:40960
	v_add_f32_e32 v106, v100, v106
	v_exp_f32_e32 v105, v113
	v_add_f32_e32 v106, v101, v106
	v_mfma_f32_32x32x16_bf16 v[2:17], v[86:89], v[230:233], v[2:17]
	v_add_f32_e32 v106, v102, v106
	v_add_f32_e32 v106, v103, v106
	v_add_f32_e32 v106, v104, v106
	v_add_f32_e32 v106, v105, v106
	v_cvt_pk_bf16_f32 v134, v239, v241
	v_mfma_f32_32x32x16_bf16 v[18:33], v[86:89], v[234:237], v[18:33]
	v_cvt_pk_bf16_f32 v135, v242, v243
	v_cvt_pk_bf16_f32 v136, v244, v245
	v_cvt_pk_bf16_f32 v137, v246, v247
	v_cvt_pk_bf16_f32 v130, v98, v99
	v_mfma_f32_32x32x16_bf16 v[34:49], v[86:89], v[168:171], v[34:49]
	v_cvt_pk_bf16_f32 v131, v100, v101
	v_cvt_pk_bf16_f32 v132, v102, v103
	v_cvt_pk_bf16_f32 v133, v104, v105
	v_add_f32_e32 v139, v139, v106
	v_mfma_f32_32x32x16_bf16 v[50:65], v[86:89], v[172:175], v[50:65]
	s_waitcnt lgkmcnt(0)
	s_barrier
	s_cbranch_scc0 .LBB0_531
	v_and_b32_e32 v82, 0x3fffffc0, v143
	v_lshl_add_u32 v143, v82, 2, 0
	ds_read_b128 v[82:85], v157 offset:40960
	ds_read_b128 v[86:89], v157 offset:45056
	s_waitcnt lgkmcnt(1)
	v_mfma_f32_32x32x16_bf16 v[98:113], v[82:85], v[126:129], 0
	s_waitcnt lgkmcnt(0)
	v_mfma_f32_32x32x16_bf16 v[82:97], v[86:89], v[126:129], 0
	ds_read_b128 v[126:129], v159 offset:40960
	ds_read_b128 v[146:149], v159 offset:45056
	s_waitcnt lgkmcnt(1)
	v_mfma_f32_32x32x16_bf16 v[98:113], v[126:129], v[122:125], v[98:113]
	s_waitcnt lgkmcnt(0)
	v_mfma_f32_32x32x16_bf16 v[82:97], v[146:149], v[122:125], v[82:97]
	ds_read_b128 v[122:125], v162 offset:40960
	ds_read_b128 v[126:129], v162 offset:45056
	s_waitcnt lgkmcnt(1)
	v_mfma_f32_32x32x16_bf16 v[98:113], v[122:125], v[118:121], v[98:113]
	s_waitcnt lgkmcnt(0)
	v_mfma_f32_32x32x16_bf16 v[82:97], v[126:129], v[118:121], v[82:97]
	ds_read_b128 v[118:121], v163 offset:40960
	ds_read_b128 v[122:125], v163 offset:45056
	ds_read_b64_tr_b16 v[126:127], v156 offset:0
	ds_read_b64_tr_b16 v[128:129], v156 offset:0x800
	s_waitcnt lgkmcnt(1)
	v_mfma_f32_32x32x16_bf16 v[98:113], v[118:121], v[114:117], v[98:113]
	ds_read_b64_tr_b16 v[118:119], v156 offset:0x200
	ds_read_b64_tr_b16 v[120:121], v156 offset:0xa00
	ds_read_b64_tr_b16 v[146:147], v156 offset:0x400
	ds_read_b64_tr_b16 v[148:149], v156 offset:0xc00
	ds_read_b64_tr_b16 v[158:159], v156 offset:0x600
	ds_read_b64_tr_b16 v[160:161], v156 offset:0xe00
	s_waitcnt lgkmcnt(0)
	s_waitcnt lgkmcnt(0)
	v_mfma_f32_32x32x16_bf16 v[82:97], v[122:125], v[114:117], v[82:97]
	v_mfma_f32_32x32x16_bf16 v[2:17], v[134:137], v[126:129], v[2:17]
	v_mfma_f32_32x32x16_bf16 v[18:33], v[134:137], v[118:121], v[18:33]
	v_mfma_f32_32x32x16_bf16 v[34:49], v[134:137], v[146:149], v[34:49]
	v_mfma_f32_32x32x16_bf16 v[50:65], v[134:137], v[158:161], v[50:65]
	v_exp_f32_e32 v66, v66
	v_exp_f32_e32 v67, v67
	v_exp_f32_e32 v68, v68
	v_exp_f32_e32 v69, v69
	v_exp_f32_e32 v70, v70
	v_add_f32_e32 v114, 0, v66
	v_exp_f32_e32 v71, v71
	v_add_f32_e32 v114, v67, v114
	v_exp_f32_e32 v72, v72
	v_add_f32_e32 v114, v68, v114
	v_exp_f32_e32 v73, v73
	v_add_f32_e32 v114, v69, v114
	v_exp_f32_e32 v74, v74
	v_add_f32_e32 v114, v70, v114
	v_exp_f32_e32 v75, v75
	v_add_f32_e32 v114, v71, v114
	v_exp_f32_e32 v76, v76
	v_add_f32_e32 v114, v72, v114
	v_exp_f32_e32 v77, v77
	v_add_f32_e32 v114, v73, v114
	v_exp_f32_e32 v78, v78
	v_add_f32_e32 v114, v74, v114
	v_exp_f32_e32 v79, v79
	v_add_f32_e32 v114, v75, v114
	v_exp_f32_e32 v80, v80
	v_add_f32_e32 v114, v76, v114
	v_exp_f32_e32 v81, v81
	v_add_f32_e32 v114, v77, v114
	v_add_f32_e32 v114, v78, v114
	v_add_f32_e32 v114, v79, v114
	v_add_f32_e32 v114, v80, v114
	v_cvt_pk_bf16_f32 v66, v66, v67
	v_cvt_pk_bf16_f32 v67, v68, v69
	v_cvt_pk_bf16_f32 v68, v70, v71
	v_cvt_pk_bf16_f32 v69, v72, v73
	v_add_f32_e32 v114, v81, v114
	v_cvt_pk_bf16_f32 v70, v74, v75
	v_cvt_pk_bf16_f32 v71, v76, v77
	v_cvt_pk_bf16_f32 v72, v78, v79
	v_cvt_pk_bf16_f32 v73, v80, v81
	v_add_f32_e32 v126, v139, v114
	ds_read_b64_tr_b16 v[74:75], v156 offset:0x1000
	ds_read_b64_tr_b16 v[76:77], v156 offset:0x1800
	ds_read_b64_tr_b16 v[78:79], v156 offset:0x1200
	ds_read_b64_tr_b16 v[80:81], v156 offset:0x1a00
	ds_read_b64_tr_b16 v[114:115], v156 offset:0x1400
	ds_read_b64_tr_b16 v[116:117], v156 offset:0x1c00
	ds_read_b64_tr_b16 v[118:119], v156 offset:0x1600
	ds_read_b64_tr_b16 v[120:121], v156 offset:0x1e00
	s_waitcnt lgkmcnt(0)
	s_nop 0
	v_mfma_f32_32x32x16_bf16 v[2:17], v[130:133], v[74:77], v[2:17]
	ds_read_b64_tr_b16 v[74:75], v156 offset:0x2000
	ds_read_b64_tr_b16 v[76:77], v156 offset:0x2800
	v_mfma_f32_32x32x16_bf16 v[18:33], v[130:133], v[78:81], v[18:33]
	ds_read_b64_tr_b16 v[78:79], v156 offset:0x2200
	ds_read_b64_tr_b16 v[80:81], v156 offset:0x2a00
	v_mfma_f32_32x32x16_bf16 v[34:49], v[130:133], v[114:117], v[34:49]
	ds_read_b64_tr_b16 v[114:115], v156 offset:0x2400
	ds_read_b64_tr_b16 v[116:117], v156 offset:0x2c00
	ds_read_b64_tr_b16 v[122:123], v156 offset:0x2600
	ds_read_b64_tr_b16 v[124:125], v156 offset:0x2e00
	s_waitcnt lgkmcnt(0)
	v_mfma_f32_32x32x16_bf16 v[50:65], v[130:133], v[118:121], v[50:65]
	v_mfma_f32_32x32x16_bf16 v[2:17], v[66:69], v[74:77], v[2:17]
	ds_read_b64_tr_b16 v[74:75], v156 offset:0x3000
	ds_read_b64_tr_b16 v[76:77], v156 offset:0x3800
	v_mfma_f32_32x32x16_bf16 v[18:33], v[66:69], v[78:81], v[18:33]
	ds_read_b64_tr_b16 v[78:79], v156 offset:0x3200
	ds_read_b64_tr_b16 v[80:81], v156 offset:0x3a00
	v_mfma_f32_32x32x16_bf16 v[34:49], v[66:69], v[114:117], v[34:49]
	ds_read_b64_tr_b16 v[114:115], v156 offset:0x3400
	ds_read_b64_tr_b16 v[116:117], v156 offset:0x3c00
	ds_read_b64_tr_b16 v[118:119], v156 offset:0x3600
	ds_read_b64_tr_b16 v[120:121], v156 offset:0x3e00
	s_waitcnt lgkmcnt(0)
; #define SBAR() __builtin_amdgcn_sched_barrier(0)
; #define SBAR() __builtin_amdgcn_sched_barrier(0)
; __device__ __forceinline__ void attn_unit(const bf16* __restrict__ Qb, const bf16* __restrict__ Kh, const bf16* __restrict__ Vh, bf16* __restrict__ Ob, int seq, char* lds) {
;     ...
;     pv_ks<1>(o, vb0, pa1); pv_ks<2>(o, vb0, pa2); pv_ks<3>(o, vb0, pa3); SBAR();
;     softHalf(pB0, l_reg, pa0, pa1); SBAR();
;     pv_ks<0>(o, vb0 + SHM_V, pa0); SBAR();
;     softHalf(pB1, l_reg, pa2, pa3); SBAR();
;     pv_ks<1>(o, vb0 + SHM_V, pa1); pv_ks<2>(o, vb0 + SHM_V, pa2); pv_ks<3>(o, vb0 + SHM_V, pa3);
;     { auto rr = __builtin_amdgcn_permlane32_swap(__float_as_uint(l_reg), __float_as_uint(l_reg), false, false); l_reg = __uint_as_float(rr[0]) + __uint_as_float(rr[1]); }
;     if (hi == 0) wsf[r32] = l_reg; asm volatile("s_waitcnt lgkmcnt(0)" ::: "memory");
	v_mfma_f32_32x32x16_bf16 v[50:65], v[66:69], v[122:125], v[50:65]
	v_mfma_f32_32x32x16_bf16 v[2:17], v[70:73], v[74:77], v[2:17]
	v_mfma_f32_32x32x16_bf16 v[18:33], v[70:73], v[78:81], v[18:33]
	v_mfma_f32_32x32x16_bf16 v[34:49], v[70:73], v[114:117], v[34:49]
	v_mfma_f32_32x32x16_bf16 v[50:65], v[70:73], v[118:121], v[50:65]
	v_exp_f32_e32 v66, v98
	v_exp_f32_e32 v67, v99
	v_exp_f32_e32 v68, v100
	v_exp_f32_e32 v69, v101
	v_exp_f32_e32 v70, v102
	v_add_f32_e32 v98, 0, v66
	v_exp_f32_e32 v71, v103
	v_add_f32_e32 v98, v67, v98
	v_exp_f32_e32 v72, v104
	v_add_f32_e32 v98, v68, v98
	v_exp_f32_e32 v73, v105
	v_add_f32_e32 v98, v69, v98
	v_exp_f32_e32 v74, v106
	v_add_f32_e32 v98, v70, v98
	v_exp_f32_e32 v75, v107
	v_add_f32_e32 v98, v71, v98
	v_exp_f32_e32 v76, v108
	v_add_f32_e32 v98, v72, v98
	v_exp_f32_e32 v77, v109
	v_add_f32_e32 v98, v73, v98
	v_exp_f32_e32 v78, v110
	v_add_f32_e32 v98, v74, v98
	v_exp_f32_e32 v79, v111
	v_add_f32_e32 v98, v75, v98
	v_exp_f32_e32 v80, v112
	v_add_f32_e32 v98, v76, v98
	v_exp_f32_e32 v81, v113
	v_add_f32_e32 v98, v77, v98
	v_add_f32_e32 v98, v78, v98
	v_add_f32_e32 v98, v79, v98
	v_add_f32_e32 v98, v80, v98
	v_cvt_pk_bf16_f32 v66, v66, v67
	v_cvt_pk_bf16_f32 v67, v68, v69
	v_cvt_pk_bf16_f32 v68, v70, v71
	v_cvt_pk_bf16_f32 v69, v72, v73
	v_add_f32_e32 v98, v81, v98
	v_cvt_pk_bf16_f32 v70, v74, v75
	v_cvt_pk_bf16_f32 v71, v76, v77
	v_cvt_pk_bf16_f32 v72, v78, v79
	v_cvt_pk_bf16_f32 v73, v80, v81
	v_add_f32_e32 v106, v126, v98
	ds_read_b64_tr_b16 v[74:75], v141 offset:0
	ds_read_b64_tr_b16 v[76:77], v141 offset:0x800
	ds_read_b64_tr_b16 v[78:79], v141 offset:0x200
	ds_read_b64_tr_b16 v[80:81], v141 offset:0xa00
	ds_read_b64_tr_b16 v[98:99], v141 offset:0x400
	ds_read_b64_tr_b16 v[100:101], v141 offset:0xc00
	ds_read_b64_tr_b16 v[102:103], v141 offset:0x600
	ds_read_b64_tr_b16 v[104:105], v141 offset:0xe00
	s_waitcnt lgkmcnt(0)
	s_nop 0
	v_mfma_f32_32x32x16_bf16 v[2:17], v[66:69], v[74:77], v[2:17]
	v_mfma_f32_32x32x16_bf16 v[18:33], v[66:69], v[78:81], v[18:33]
	v_mfma_f32_32x32x16_bf16 v[34:49], v[66:69], v[98:101], v[34:49]
	v_mfma_f32_32x32x16_bf16 v[50:65], v[66:69], v[102:105], v[50:65]
	v_exp_f32_e32 v67, v82
	v_exp_f32_e32 v68, v83
	v_exp_f32_e32 v69, v84
	v_exp_f32_e32 v75, v85
	v_exp_f32_e32 v76, v86
	v_add_f32_e32 v66, 0, v67
	v_exp_f32_e32 v77, v87
	v_add_f32_e32 v66, v68, v66
	v_exp_f32_e32 v78, v88
	v_add_f32_e32 v66, v69, v66
	v_exp_f32_e32 v79, v89
	v_add_f32_e32 v66, v75, v66
	v_exp_f32_e32 v80, v90
	v_add_f32_e32 v66, v76, v66
	v_exp_f32_e32 v81, v91
	v_add_f32_e32 v66, v77, v66
	v_exp_f32_e32 v82, v92
	v_add_f32_e32 v66, v78, v66
	v_exp_f32_e32 v83, v93
	v_add_f32_e32 v66, v79, v66
	v_exp_f32_e32 v84, v94
	v_add_f32_e32 v66, v80, v66
	v_exp_f32_e32 v85, v95
	v_add_f32_e32 v66, v81, v66
	v_exp_f32_e32 v86, v96
	v_add_f32_e32 v66, v82, v66
	v_exp_f32_e32 v87, v97
	v_add_f32_e32 v66, v83, v66
	v_add_f32_e32 v66, v84, v66
	v_add_f32_e32 v66, v85, v66
	v_add_f32_e32 v66, v86, v66
	v_add_f32_e32 v66, v87, v66
	v_add_f32_e32 v66, v66, v106
	v_cvt_pk_bf16_f32 v74, v67, v68
	v_cvt_pk_bf16_f32 v75, v69, v75
	v_cvt_pk_bf16_f32 v76, v76, v77
	v_cvt_pk_bf16_f32 v77, v78, v79
	v_cvt_pk_bf16_f32 v78, v80, v81
	v_cvt_pk_bf16_f32 v79, v82, v83
	v_cvt_pk_bf16_f32 v80, v84, v85
	v_cvt_pk_bf16_f32 v81, v86, v87
	s_nop 0
	ds_read_b64_tr_b16 v[82:83], v141 offset:0x1000
	ds_read_b64_tr_b16 v[84:85], v141 offset:0x1800
	ds_read_b64_tr_b16 v[86:87], v141 offset:0x1200
	ds_read_b64_tr_b16 v[88:89], v141 offset:0x1a00
	ds_read_b64_tr_b16 v[90:91], v141 offset:0x1400
	ds_read_b64_tr_b16 v[92:93], v141 offset:0x1c00
	ds_read_b64_tr_b16 v[94:95], v141 offset:0x1600
	ds_read_b64_tr_b16 v[96:97], v141 offset:0x1e00
	s_waitcnt lgkmcnt(0)
	s_nop 0
	v_mfma_f32_32x32x16_bf16 v[2:17], v[70:73], v[82:85], v[2:17]
	ds_read_b64_tr_b16 v[82:83], v141 offset:0x2000
	ds_read_b64_tr_b16 v[84:85], v141 offset:0x2800
	v_mfma_f32_32x32x16_bf16 v[18:33], v[70:73], v[86:89], v[18:33]
	ds_read_b64_tr_b16 v[86:87], v141 offset:0x2200
	ds_read_b64_tr_b16 v[88:89], v141 offset:0x2a00
	v_mfma_f32_32x32x16_bf16 v[34:49], v[70:73], v[90:93], v[34:49]
	ds_read_b64_tr_b16 v[90:91], v141 offset:0x2400
	ds_read_b64_tr_b16 v[92:93], v141 offset:0x2c00
	ds_read_b64_tr_b16 v[98:99], v141 offset:0x2600
	ds_read_b64_tr_b16 v[100:101], v141 offset:0x2e00
	s_waitcnt lgkmcnt(0)
	v_mfma_f32_32x32x16_bf16 v[50:65], v[70:73], v[94:97], v[50:65]
	ds_read_b64_tr_b16 v[68:69], v141 offset:0x3000
	ds_read_b64_tr_b16 v[70:71], v141 offset:0x3800
	v_mfma_f32_32x32x16_bf16 v[2:17], v[74:77], v[82:85], v[2:17]
	ds_read_b64_tr_b16 v[82:83], v141 offset:0x3200
	ds_read_b64_tr_b16 v[84:85], v141 offset:0x3a00
	v_mfma_f32_32x32x16_bf16 v[18:33], v[74:77], v[86:89], v[18:33]
	ds_read_b64_tr_b16 v[86:87], v141 offset:0x3400
	ds_read_b64_tr_b16 v[88:89], v141 offset:0x3c00
	v_mfma_f32_32x32x16_bf16 v[34:49], v[74:77], v[90:93], v[34:49]
	ds_read_b64_tr_b16 v[90:91], v141 offset:0x3600
	ds_read_b64_tr_b16 v[92:93], v141 offset:0x3e00
	s_waitcnt lgkmcnt(0)
	v_mfma_f32_32x32x16_bf16 v[50:65], v[74:77], v[98:101], v[50:65]
	v_mfma_f32_32x32x16_bf16 v[2:17], v[78:81], v[68:71], v[2:17]
	v_mov_b32_e32 v67, v66
	s_nop 1
	v_permlane32_swap_b32_e32 v66, v67
	v_cmp_gt_u32_e32 vcc, 32, v145
	v_mfma_f32_32x32x16_bf16 v[18:33], v[78:81], v[82:85], v[18:33]
	v_mfma_f32_32x32x16_bf16 v[34:49], v[78:81], v[86:89], v[34:49]
	v_mfma_f32_32x32x16_bf16 v[50:65], v[78:81], v[90:93], v[50:65]
	s_and_saveexec_b64 s[10:11], vcc
	s_cbranch_execz .LBB0_529
	v_add_f32_e32 v66, v66, v67
	v_lshl_add_u32 v67, v153, 2, v143
	ds_write_b32 v67, v66 offset:49152
	s_branch .LBB0_529
